# E25lo: strategy 4 mirror: static s_setprio 1 for waves 0-3 at entry, all per-segment flips removed; on E23
# speedup vs baseline: 1.0020x; 1.0020x over previous
_Z6mk_fwd4Args:
	v_readfirstlane_b32 s3, v0
	s_nop 3
	s_lshr_b32 s3, s3, 6
	s_and_b32 s3, s3, 15
	s_cmp_ge_u32 s3, 4
	s_cbranch_scc1 .Lgk_prio_done
	s_setprio 1
